# P0->P1 seam: single-counter grid sync replaced by a one-shot two-level barrier (8 groups of 32 workgroups) on the per-launch-zeroed counter words
# speedup vs baseline: 1.0666x; 1.0099x over previous
; #define LAS __attribute__((address_space(3)))
; #define PH_IDS() int tid = threadIdx.x; asm volatile("" : "+v"(tid)); const int lane = tid & 63
; #define SEAM(k) do { if (IN(k) && IN((k) + 1)) { if ((k) == 0) cg::this_grid().sync(); else xcd_barrier(xbar); } } while (0)
; __global__ void __launch_bounds__(NWAVES * 64, 2) fwd_mega(Args args) {
;     ...
;     { volatile LAS unsigned* m_ = (volatile LAS unsigned*)(lds + MISC_OFF); if (threadIdx.x < 16) m_[threadIdx.x] = 0u; }
;     __syncthreads();
;     if (lo == 0) { unsigned* bz = (unsigned*)(ws + WS_BAR); for (int i = blockIdx.x * (NWAVES * 64) + threadIdx.x; i < BAR_BYTES / 4; i += gridDim.x * (NWAVES * 64)) bz[i] = 0u; }
;     XcdBarrier xbar; xbar.bar = (unsigned*)(ws + WS_BAR); xbar.x = 0; xbar.st = (volatile LAS unsigned*)(lds + MISC_OFF);
;     bf16* XN = (bf16*)args.out;
;     bf16* AO = (bf16*)(ws + WS_AO); bf16* VA = (bf16*)(ws + WS_VA); bf16* ZA = (bf16*)(ws + WS_ZA); bf16* KB = (bf16*)(ws + WS_K); bf16* VB = (bf16*)(ws + WS_V); bf16* ZB = (bf16*)(ws + WS_ZB);
;     bf16* GA = VA; bf16* GB = ZA; bf16* MG = KB;
;     float* ssq = (float*)(ws + WS_SSQ); float* logf_ = (float*)(ws + WS_LOGF); float* cc = (float*)(ws + WS_CC);
;     if (IN(0)) { PH_IDS(); p0_prologue(args, lds, vcu, G, tid, lane, wave); __syncthreads(); }
;     SEAM(0);
.LBB0_62:
	s_cmp_gt_i32 s31, 1
	s_cselect_b64 s[4:5], -1, 0
	s_and_b64 s[0:1], s[22:23], s[4:5]
	s_andn2_b64 vcc, exec, s[0:1]
	v_cmp_eq_u32_e64 s[0:1], 0, v0
	s_cbranch_vccnz .LBB0_74
	s_barrier
	s_and_saveexec_b64 s[6:7], s[0:1]
	s_cbranch_execz .LBB0_73
	buffer_wbl2 sc1
	s_waitcnt vmcnt(0)
	s_add_u32 s8, s28, 0x84000
	s_addc_u32 s9, s29, 0
	s_and_b32 s10, s2, 7
	s_lshl_b32 s10, s10, 8
	s_add_u32 s10, s8, s10
	s_addc_u32 s11, s9, 0
	v_mov_b32_e32 v1, 0
	v_mov_b32_e32 v2, 1
	global_atomic_add v3, v1, v2, s[10:11] offset:32 sc0
	s_waitcnt vmcnt(0)
	v_readfirstlane_b32 s12, v3
	s_cmp_lg_u32 s12, 31
	s_cbranch_scc1 .Lgs_member
	global_atomic_add v3, v1, v2, s[8:9] offset:2080 sc0
	s_waitcnt vmcnt(0)
	v_readfirstlane_b32 s12, v3
	s_cmp_lg_u32 s12, 7
	s_cbranch_scc1 .Lgs_leader_wait
	global_atomic_add v1, v2, s[8:9] offset:2112
	s_branch .Lgs_leader_go
.Lgs_leader_wait:
	s_mov_b32 s13, 0
.Lgs_top:
	s_sleep 1
	global_load_dword v3, v1, s[8:9] offset:2112 sc1
	s_waitcnt vmcnt(0)
	v_readfirstlane_b32 s12, v3
	s_add_u32 s13, s13, 1
	s_cmp_lg_u32 s12, 0
	s_cbranch_scc1 .Lgs_top_ok
	s_cmp_lt_u32 s13, 0x4000
	s_cbranch_scc1 .Lgs_top
.Lgs_top_ok:
.Lgs_leader_go:
	global_atomic_add v1, v2, s[10:11] offset:64
	s_branch .Lgs_done

; #define LAS __attribute__((address_space(3)))
; #define PH_IDS() int tid = threadIdx.x; asm volatile("" : "+v"(tid)); const int lane = tid & 63
; #define SEAM(k) do { if (IN(k) && IN((k) + 1)) { if ((k) == 0) cg::this_grid().sync(); else xcd_barrier(xbar); } } while (0)
; __global__ void __launch_bounds__(NWAVES * 64, 2) fwd_mega(Args args) {
;     ...
;     { volatile LAS unsigned* m_ = (volatile LAS unsigned*)(lds + MISC_OFF); if (threadIdx.x < 16) m_[threadIdx.x] = 0u; }
;     __syncthreads();
;     if (lo == 0) { unsigned* bz = (unsigned*)(ws + WS_BAR); for (int i = blockIdx.x * (NWAVES * 64) + threadIdx.x; i < BAR_BYTES / 4; i += gridDim.x * (NWAVES * 64)) bz[i] = 0u; }
;     XcdBarrier xbar; xbar.bar = (unsigned*)(ws + WS_BAR); xbar.x = 0; xbar.st = (volatile LAS unsigned*)(lds + MISC_OFF);
;     bf16* XN = (bf16*)args.out;
;     bf16* AO = (bf16*)(ws + WS_AO); bf16* VA = (bf16*)(ws + WS_VA); bf16* ZA = (bf16*)(ws + WS_ZA); bf16* KB = (bf16*)(ws + WS_K); bf16* VB = (bf16*)(ws + WS_V); bf16* ZB = (bf16*)(ws + WS_ZB);
;     bf16* GA = VA; bf16* GB = ZA; bf16* MG = KB;
;     float* ssq = (float*)(ws + WS_SSQ); float* logf_ = (float*)(ws + WS_LOGF); float* cc = (float*)(ws + WS_CC);
;     if (IN(0)) { PH_IDS(); p0_prologue(args, lds, vcu, G, tid, lane, wave); __syncthreads(); }
;     SEAM(0);
.Lgs_grp:
	s_sleep 1
	global_load_dword v3, v1, s[10:11] offset:64 sc1
	s_waitcnt vmcnt(0)
	v_readfirstlane_b32 s12, v3
	s_add_u32 s13, s13, 1
	s_cmp_lg_u32 s12, 0
	s_cbranch_scc1 .Lgs_grp_ok
	s_cmp_lt_u32 s13, 0x4000
	s_cbranch_scc1 .Lgs_grp
.Lgs_grp_ok:
.Lgs_done:
	s_waitcnt vmcnt(0)
.LBB0_72:
	buffer_inv sc1
	s_waitcnt vmcnt(0)
